# also MoBA layer3 tile loop restructured the same way (both MoBA layers now)
# speedup vs baseline: 1.0287x; 1.0143x over previous
; #define ATT_LAS __attribute__((address_space(3)))
; #define ATT_MFMA(a, b, c) __builtin_amdgcn_mfma_f32_32x32x16_bf16((a), (b), (c), 0, 0, 0)
; __device__ __forceinline__ void qkt(f32x16& p0, f32x16& p1, lds_cptr kb, const bf16x8* qr, const f32x16& z) {
; #pragma unroll
;     for (int d0 = 0; d0 < 4; ++d0) {
;         const bf16x8 b0 = *(const ATT_LAS bf16x8*)(kb + d0 * 2048);
;         const bf16x8 b1 = *(const ATT_LAS bf16x8*)(kb + d0 * 2048 + 512);
;         if (d0 == 0) { p0 = ATT_MFMA(b0, qr[0], z); p1 = ATT_MFMA(b1, qr[0], z); }
.LBB0_2386:
	s_add_i32 s36, s43, 0x2000
	s_and_b32 s42, s36, 0x6000
	v_add_u32_e32 v133, s42, v130
	s_and_b32 s42, s43, 0x6000
	ds_read_b128 v[154:157], v133
	ds_read_b128 v[158:161], v133 offset:512
	ds_read_b128 v[162:165], v133 offset:2048
	ds_read_b128 v[166:169], v133 offset:2560
	ds_read_b128 v[170:173], v133 offset:4096
	ds_read_b128 v[174:177], v133 offset:4608
	ds_read_b128 v[178:181], v133 offset:6144
	ds_read_b128 v[182:185], v133 offset:6656
	v_add_u32_e32 v218, s42, v132
	ds_read_b64_tr_b16 v[186:187], v218
	ds_read_b64_tr_b16 v[188:189], v218 offset:512
	ds_read_b64_tr_b16 v[190:191], v218 offset:1024
	ds_read_b64_tr_b16 v[192:193], v218 offset:1536
	ds_read_b64_tr_b16 v[194:195], v218 offset:2048
	ds_read_b64_tr_b16 v[196:197], v218 offset:2560
	ds_read_b64_tr_b16 v[198:199], v218 offset:3072
	ds_read_b64_tr_b16 v[200:201], v218 offset:3584
	s_cmp_ge_i32 s30, s29
	s_cselect_b64 s[10:11], -1, 0
	s_cbranch_scc1 .Lmb3_near
	s_lshr_b32 s42, s30, 2
	v_lshrrev_b32_e32 v219, s42, v129
	v_and_b32_e32 v219, 1, v219
	v_cmp_eq_u32_e32 vcc, 1, v219
	s_nop 1
	v_cndmask_b32_e32 v219, v126, v128, vcc
	v_add_f32_e32 v48, v0, v219
	v_add_f32_e32 v49, v1, v219
	v_add_f32_e32 v50, v2, v219
	v_add_f32_e32 v51, v3, v219
	v_add_f32_e32 v52, v4, v219
	v_add_f32_e32 v53, v5, v219
	v_add_f32_e32 v54, v6, v219
	v_add_f32_e32 v55, v7, v219
	v_add_f32_e32 v56, v8, v219
	v_add_f32_e32 v57, v9, v219
	v_add_f32_e32 v58, v10, v219
	v_add_f32_e32 v59, v11, v219
	v_add_f32_e32 v60, v12, v219
	v_add_f32_e32 v61, v13, v219
	v_add_f32_e32 v62, v14, v219
	v_add_f32_e32 v63, v15, v219
	s_branch .Lmb3_qk

; #define ATT_LAS __attribute__((address_space(3)))
; #define ATT_MFMA(a, b, c) __builtin_amdgcn_mfma_f32_32x32x16_bf16((a), (b), (c), 0, 0, 0)
; __device__ __forceinline__ void qkt(f32x16& p0, f32x16& p1, lds_cptr kb, const bf16x8* qr, const f32x16& z) {
; #pragma unroll
;     for (int d0 = 0; d0 < 4; ++d0) {
;         const bf16x8 b0 = *(const ATT_LAS bf16x8*)(kb + d0 * 2048);
;         const bf16x8 b1 = *(const ATT_LAS bf16x8*)(kb + d0 * 2048 + 512);
;         if (d0 == 0) { p0 = ATT_MFMA(b0, qr[0], z); p1 = ATT_MFMA(b1, qr[0], z); }
;         else { p0 = ATT_MFMA(b0, qr[d0], p0); p1 = ATT_MFMA(b1, qr[d0], p1); } }
; }
; __device__ __forceinline__ void pv(f32x16* o, int vb, bf16x8 pa0, bf16x8 pa1, bf16x8 pa2, bf16x8 pa3) {
; #pragma unroll
;     for (int d0 = 0; d0 < 2; ++d0) { s16x4 lo[4], hi[4];
; #pragma unroll
;         for (int ks = 0; ks < 4; ++ks) {
;             asm volatile("ds_read_b64_tr_b16 %0,%1 offset:%c2" : "=&v"(lo[ks]) : "v"(vb), "i"(d0 * 4096 + ks * 1024) : "memory");
;             asm volatile("ds_read_b64_tr_b16 %0,%1 offset:%c2" : "=&v"(hi[ks]) : "v"(vb), "i"(d0 * 4096 + ks * 1024 + 512) : "memory"); }
;         asm volatile("s_waitcnt lgkmcnt(0)" ::: "memory"); __builtin_amdgcn_sched_barrier(0);
;     ...
;         o[d0] = ATT_MFMA(pa0, ATT_PK(0), o[d0]);
;         o[d0] = ATT_MFMA(pa1, ATT_PK(1), o[d0]);
;         o[d0] = ATT_MFMA(pa2, ATT_PK(2), o[d0]);
;         o[d0] = ATT_MFMA(pa3, ATT_PK(3), o[d0]);
;     ...
;     }
; }
.Lmb3_qk:
	s_nop 1
	s_waitcnt lgkmcnt(14)
	v_mfma_f32_32x32x16_bf16 v[64:79], v[154:157], v[92:95], v[48:63]
	v_mfma_f32_32x32x16_bf16 v[48:63], v[158:161], v[92:95], v[48:63]
	s_waitcnt lgkmcnt(12)
	v_mfma_f32_32x32x16_bf16 v[64:79], v[162:165], v[88:91], v[64:79]
	v_mfma_f32_32x32x16_bf16 v[48:63], v[166:169], v[88:91], v[48:63]
	s_waitcnt lgkmcnt(10)
	v_mfma_f32_32x32x16_bf16 v[64:79], v[170:173], v[84:87], v[64:79]
	v_mfma_f32_32x32x16_bf16 v[48:63], v[174:177], v[84:87], v[48:63]
	s_waitcnt lgkmcnt(8)
	v_mfma_f32_32x32x16_bf16 v[64:79], v[178:181], v[80:83], v[64:79]
	v_mfma_f32_32x32x16_bf16 v[48:63], v[182:185], v[80:83], v[48:63]
	ds_read_b64_tr_b16 v[202:203], v218 offset:4096
	ds_read_b64_tr_b16 v[204:205], v218 offset:4608
	ds_read_b64_tr_b16 v[206:207], v218 offset:5120
	ds_read_b64_tr_b16 v[208:209], v218 offset:5632
	ds_read_b64_tr_b16 v[210:211], v218 offset:6144
	ds_read_b64_tr_b16 v[212:213], v218 offset:6656
	ds_read_b64_tr_b16 v[214:215], v218 offset:7168
	ds_read_b64_tr_b16 v[216:217], v218 offset:7680
	s_waitcnt lgkmcnt(14)
	v_mfma_f32_32x32x16_bf16 v[16:31], v[108:111], v[186:189], v[16:31]
	s_waitcnt lgkmcnt(12)
	v_mfma_f32_32x32x16_bf16 v[16:31], v[104:107], v[190:193], v[16:31]
	s_waitcnt lgkmcnt(10)
	v_mfma_f32_32x32x16_bf16 v[16:31], v[100:103], v[194:197], v[16:31]
	s_waitcnt lgkmcnt(8)
	v_mfma_f32_32x32x16_bf16 v[16:31], v[96:99], v[198:201], v[16:31]
	s_waitcnt lgkmcnt(6)
	v_mfma_f32_32x32x16_bf16 v[32:47], v[108:111], v[202:205], v[32:47]
	s_waitcnt lgkmcnt(4)
	v_mfma_f32_32x32x16_bf16 v[32:47], v[104:107], v[206:209], v[32:47]
	s_waitcnt lgkmcnt(2)
	v_mfma_f32_32x32x16_bf16 v[32:47], v[100:103], v[210:213], v[32:47]
	s_waitcnt lgkmcnt(0)
	v_mfma_f32_32x32x16_bf16 v[32:47], v[96:99], v[214:217], v[32:47]
	s_barrier
	s_andn2_b64 vcc, exec, s[10:11]
	s_cbranch_vccnz .Lmb3_exp
	s_lshr_b32 s42, s30, 2
	s_cmp_eq_u32 s42, s93
	s_cselect_b64 s[10:11], -1, 0
	s_lshl_b32 s42, 1, s42
	v_and_b32_e32 v96, s42, v129
	v_cmp_ne_u32_e32 vcc, 0, v96
	s_or_b64 vcc, s[10:11], vcc
	s_nop 0
	v_cndmask_b32_e32 v96, v127, v112, vcc
	v_lshl_add_u32 v96, v96, 2, 0
	v_add_u32_e32 v104, 0x1d000, v96
	ds_read2_b32 v[96:97], v104 offset0:58 offset1:59
	ds_read2_b32 v[98:99], v104 offset0:26 offset1:27
	ds_read2_b32 v[100:101], v104 offset0:56 offset1:57
	s_waitcnt lgkmcnt(2)
	v_pk_add_f32 v[64:65], v[64:65], v[96:97] op_sel:[0,1] op_sel_hi:[1,0]
	ds_read2_b32 v[96:97], v104 offset0:24 offset1:25
	s_waitcnt lgkmcnt(2)
	v_pk_add_f32 v[48:49], v[48:49], v[98:99] op_sel:[0,1] op_sel_hi:[1,0]
	ds_read2_b32 v[98:99], v104 offset0:50 offset1:51
	s_waitcnt lgkmcnt(2)
	v_pk_add_f32 v[66:67], v[66:67], v[100:101] op_sel:[0,1] op_sel_hi:[1,0]
	ds_read2_b32 v[100:101], v104 offset0:18 offset1:19
	s_waitcnt lgkmcnt(1)
	v_pk_add_f32 v[68:69], v[68:69], v[98:99] op_sel:[0,1] op_sel_hi:[1,0]
	ds_read2_b32 v[98:99], v104 offset0:16 offset1:17
	s_waitcnt lgkmcnt(1)
	v_pk_add_f32 v[52:53], v[52:53], v[100:101] op_sel:[0,1] op_sel_hi:[1,0]
	ds_read2_b32 v[100:101], v104 offset0:42 offset1:43
	v_pk_add_f32 v[50:51], v[50:51], v[96:97] op_sel:[0,1] op_sel_hi:[1,0]
	ds_read2_b32 v[96:97], v104 offset0:48 offset1:49
	s_waitcnt lgkmcnt(1)
	v_pk_add_f32 v[72:73], v[72:73], v[100:101] op_sel:[0,1] op_sel_hi:[1,0]
	ds_read2_b32 v[100:101], v104 offset0:8 offset1:9
	s_waitcnt lgkmcnt(1)
	v_pk_add_f32 v[70:71], v[70:71], v[96:97] op_sel:[0,1] op_sel_hi:[1,0]
	ds_read2_b32 v[96:97], v104 offset0:10 offset1:11
	v_pk_add_f32 v[54:55], v[54:55], v[98:99] op_sel:[0,1] op_sel_hi:[1,0]
	ds_read2_b32 v[98:99], v104 offset0:40 offset1:41
	s_waitcnt lgkmcnt(2)
	v_pk_add_f32 v[58:59], v[58:59], v[100:101] op_sel:[0,1] op_sel_hi:[1,0]
	s_waitcnt lgkmcnt(1)
	v_pk_add_f32 v[56:57], v[56:57], v[96:97] op_sel:[0,1] op_sel_hi:[1,0]
	ds_read2_b32 v[96:97], v104 offset0:34 offset1:35
	s_waitcnt lgkmcnt(1)
	v_pk_add_f32 v[74:75], v[74:75], v[98:99] op_sel:[0,1] op_sel_hi:[1,0]
	ds_read2_b32 v[98:99], v104 offset0:2 offset1:3
	ds_read2_b32 v[102:103], v104 offset0:32 offset1:33
	ds_read2_b32 v[104:105], v104 offset1:1
	s_waitcnt lgkmcnt(3)
	v_pk_add_f32 v[76:77], v[76:77], v[96:97] op_sel:[0,1] op_sel_hi:[1,0]
	s_waitcnt lgkmcnt(2)
	v_pk_add_f32 v[60:61], v[60:61], v[98:99] op_sel:[0,1] op_sel_hi:[1,0]
	s_waitcnt lgkmcnt(1)
	v_pk_add_f32 v[78:79], v[78:79], v[102:103] op_sel:[0,1] op_sel_hi:[1,0]
	s_waitcnt lgkmcnt(0)
	v_pk_add_f32 v[62:63], v[62:63], v[104:105] op_sel:[0,1] op_sel_hi:[1,0]
.Lmb3_exp:
	v_exp_f32_e32 v64, v64
	v_exp_f32_e32 v48, v48
	v_exp_f32_e32 v65, v65
	v_exp_f32_e32 v49, v49
	v_exp_f32_e32 v66, v66
	v_exp_f32_e32 v50, v50
	v_exp_f32_e32 v67, v67
	v_exp_f32_e32 v51, v51
	v_add_f32_e32 v96, v48, v64
	v_exp_f32_e32 v68, v68
	v_exp_f32_e32 v52, v52
	v_add_f32_e32 v96, 0, v96
	v_add_f32_e32 v97, v49, v65
	v_exp_f32_e32 v69, v69
	v_exp_f32_e32 v53, v53
	v_add_f32_e32 v96, v97, v96
	v_add_f32_e32 v97, v50, v66
	v_exp_f32_e32 v70, v70
	v_exp_f32_e32 v54, v54
	v_add_f32_e32 v96, v97, v96
	v_add_f32_e32 v97, v51, v67
	v_exp_f32_e32 v71, v71
	v_exp_f32_e32 v55, v55
	v_add_f32_e32 v96, v97, v96
	v_add_f32_e32 v97, v52, v68
	v_exp_f32_e32 v72, v72
	v_exp_f32_e32 v56, v56
	v_add_f32_e32 v96, v97, v96
	v_add_f32_e32 v97, v53, v69
	v_exp_f32_e32 v73, v73
	v_exp_f32_e32 v57, v57
	v_add_f32_e32 v96, v97, v96
	v_add_f32_e32 v97, v54, v70
	v_exp_f32_e32 v74, v74
	v_exp_f32_e32 v58, v58
	v_add_f32_e32 v96, v97, v96
	v_add_f32_e32 v97, v55, v71
	v_exp_f32_e32 v75, v75
	v_exp_f32_e32 v59, v59
	v_add_f32_e32 v96, v97, v96
	v_add_f32_e32 v97, v56, v72
	v_exp_f32_e32 v76, v76
	v_exp_f32_e32 v60, v60
	v_add_f32_e32 v96, v97, v96
	v_add_f32_e32 v97, v57, v73
	v_exp_f32_e32 v77, v77
	v_exp_f32_e32 v61, v61
	v_add_f32_e32 v96, v97, v96
	v_add_f32_e32 v97, v58, v74
	v_exp_f32_e32 v78, v78
	v_exp_f32_e32 v62, v62
	v_add_f32_e32 v96, v97, v96
	v_add_f32_e32 v97, v59, v75
	v_exp_f32_e32 v79, v79
	v_exp_f32_e32 v63, v63
	v_add_f32_e32 v96, v97, v96
	v_add_f32_e32 v97, v60, v76
	v_add_f32_e32 v96, v97, v96
	v_add_f32_e32 v97, v61, v77
	v_add_f32_e32 v96, v97, v96
	v_add_f32_e32 v97, v62, v78
	v_add_f32_e32 v96, v97, v96
	v_add_f32_e32 v97, v63, v79
	v_add_f32_e32 v96, v97, v96
	v_add_f32_e32 v131, v131, v96
	v_cvt_pk_bf16_f32 v108, v64, v65
	v_cvt_pk_bf16_f32 v109, v66, v67
	v_cvt_pk_bf16_f32 v110, v68, v69
	v_cvt_pk_bf16_f32 v111, v70, v71
	v_cvt_pk_bf16_f32 v104, v72, v73
	v_cvt_pk_bf16_f32 v105, v74, v75
	v_cvt_pk_bf16_f32 v106, v76, v77
	v_cvt_pk_bf16_f32 v107, v78, v79
	v_cvt_pk_bf16_f32 v100, v48, v49
	v_cvt_pk_bf16_f32 v101, v50, v51
	v_cvt_pk_bf16_f32 v102, v52, v53
	v_cvt_pk_bf16_f32 v103, v54, v55
	v_cvt_pk_bf16_f32 v96, v56, v57
	v_cvt_pk_bf16_f32 v97, v58, v59
	v_cvt_pk_bf16_f32 v98, v60, v61
	v_cvt_pk_bf16_f32 v99, v62, v63
	v_lshl_add_u64 v[114:115], v[114:115], 0, s[20:21]
	v_subrev_u32_e32 v112, 64, v112
	v_lshl_add_u64 v[116:117], v[116:117], 0, s[20:21]
	s_add_i32 s30, s30, 1
	s_cmp_gt_i32 s37, 1
	s_cbranch_scc1 .Lmb3_w2
	s_cmp_lg_u32 s37, 1
	s_cbranch_scc1 .Lmb3_w0
	s_waitcnt vmcnt(1) lgkmcnt(0)
	s_barrier
	s_branch .Lmb3_bdone

; template <int MODE> __device__ __forceinline__ void attn_unit(int b, int h, int qb, int t_lo, const bf16_t* Q, const bf16_t* __restrict__ K, const bf16_t* __restrict__ V, bf16_t* O, ATT_LAS unsigned char* lds, const int wid, const float kn2, const float bmax) {
;     ...
; #pragma unroll 1
;     for (int j = 0; j < n - 1; ++j) ATT_ITER(j, true, true);
.Lmb3_bdone:
	s_cmp_lg_u32 s35, s34
	s_cbranch_scc0 .LBB0_2399
	s_mov_b32 s43, s36
	s_add_i32 s35, s30, -1
	s_cmp_ge_u32 s35, s28
	s_mov_b32 s37, 0
	s_cbranch_scc0 .LBB0_2383
	s_branch .LBB0_2384
